# fox: LDS staging write+barrier for the next tile moved to mid-tile (before exp/PV) so K reads of the next tile are not behind a barrier
# baseline (speedup 1.0000x reference)
; #define LAS __attribute__((address_space(3)))
; #define STAGE_TILE(bufi, KR, VR) do { LAS bf16_t* Ks_ = (LAS bf16_t*)(lds + (bufi) * 18432); LAS bf16_t* Vs_ = (LAS bf16_t*)(lds + (bufi) * 18432 + 9216); \
;         *(LAS u32x4*)(Ks_ + skr * 72 + sch * 8) = KR; *(LAS u32x4*)(Vs_ + skr * 72 + sch * 8) = VR; } while (0)
; #define LOAD_TILE(KR, VR, tl) do { KR = *(const GAS u32x4*)(kg + (size_t)(tl) * 64 * LDH); VR = *(const GAS u32x4*)(vg + (size_t)(tl) * 64 * LDH); } while (0)
; template <int MODE> ...
;     ...
;         STAGE_TILE(1, kB, vB);
;         __syncthreads();
;         if (MODE == 1) { const u32x4 fa = *(const LAS u32x4*)flags, fb = *(const LAS u32x4*)(flags + 4); if ((fa.x & fa.y & fa.z & fa.w & fb.x & fb.y & fb.z & fb.w) != 0u) break; }
;         LOAD_TILE(kB, vB, TILE_OF(min(it + 3, ntiles - 1)));
.LBB0_831:
	s_add_i32 s4, s13, 3
	s_min_i32 s4, s4, s10
	s_mul_i32 s4, s4, 0x62000
	s_mov_b32 s5, 0
	v_lshl_add_u64 v[176:177], s[4:5], 0, v[98:99]
	s_waitcnt vmcnt(3)
	ds_write_b128 v107, v[82:85] offset:18432
	s_waitcnt vmcnt(2)
	ds_write_b128 v107, v[86:89] offset:27648
	s_waitcnt lgkmcnt(0)
	s_barrier
	global_load_dwordx4 v[82:85], v[176:177], off offset:768
	global_load_dwordx4 v[86:89], v[176:177], off offset:1536
	v_exp_f32_e32 v34, v34
	v_exp_f32_e32 v35, v35
	v_exp_f32_e32 v36, v36
	v_exp_f32_e32 v37, v37
	v_exp_f32_e32 v38, v38
	v_exp_f32_e32 v39, v39
	v_exp_f32_e32 v40, v40
	v_exp_f32_e32 v41, v41
	v_add_f32_e32 v104, v34, v35
	v_add_f32_e32 v106, v36, v37
	v_add_f32_e32 v104, v104, v38
	v_add_f32_e32 v106, v106, v39
	v_add_f32_e32 v104, v104, v40
	v_add_f32_e32 v106, v106, v41
	v_cvt_pk_bf16_f32 v132, v34, v35
	v_cvt_pk_bf16_f32 v133, v36, v37
	v_cvt_pk_bf16_f32 v134, v38, v39
	v_cvt_pk_bf16_f32 v135, v40, v41
	v_exp_f32_e32 v42, v42
	v_exp_f32_e32 v43, v43
	s_waitcnt lgkmcnt(0)
	v_mfma_f32_32x32x16_bf16 v[18:33], v[198:201], v[132:135], v[18:33]
	v_mfma_f32_32x32x16_bf16 v[2:17], v[214:217], v[132:135], v[2:17]
	v_exp_f32_e32 v44, v44
	v_exp_f32_e32 v45, v45
	v_exp_f32_e32 v46, v46
	v_exp_f32_e32 v47, v47
	v_exp_f32_e32 v48, v48
	v_exp_f32_e32 v49, v49
	v_add_f32_e32 v104, v104, v42
	v_add_f32_e32 v106, v106, v43
	v_add_f32_e32 v104, v104, v44
	v_add_f32_e32 v106, v106, v45
	v_add_f32_e32 v104, v104, v46
	v_add_f32_e32 v106, v106, v47
	v_add_f32_e32 v104, v104, v48
	v_add_f32_e32 v106, v106, v49
	v_cvt_pk_bf16_f32 v148, v42, v43
	v_cvt_pk_bf16_f32 v149, v44, v45
	v_cvt_pk_bf16_f32 v150, v46, v47
	v_cvt_pk_bf16_f32 v151, v48, v49
	v_exp_f32_e32 v50, v50
	v_exp_f32_e32 v51, v51
	v_mfma_f32_32x32x16_bf16 v[18:33], v[202:205], v[148:151], v[18:33]
	v_mfma_f32_32x32x16_bf16 v[2:17], v[218:221], v[148:151], v[2:17]
	v_exp_f32_e32 v52, v52
	v_exp_f32_e32 v53, v53
	v_exp_f32_e32 v54, v54
	v_exp_f32_e32 v55, v55
	v_exp_f32_e32 v56, v56
	v_exp_f32_e32 v57, v57
	v_add_f32_e32 v104, v104, v50
	v_add_f32_e32 v106, v106, v51
	v_add_f32_e32 v104, v104, v52
	v_add_f32_e32 v106, v106, v53
	v_add_f32_e32 v104, v104, v54
	v_add_f32_e32 v106, v106, v55
	v_add_f32_e32 v104, v104, v56
	v_add_f32_e32 v106, v106, v57
	v_cvt_pk_bf16_f32 v156, v50, v51
	v_cvt_pk_bf16_f32 v157, v52, v53
	v_cvt_pk_bf16_f32 v158, v54, v55
	v_cvt_pk_bf16_f32 v159, v56, v57
	v_exp_f32_e32 v58, v58
	v_exp_f32_e32 v59, v59
	v_mfma_f32_32x32x16_bf16 v[18:33], v[206:209], v[156:159], v[18:33]
	v_mfma_f32_32x32x16_bf16 v[2:17], v[234:237], v[156:159], v[2:17]
	v_exp_f32_e32 v60, v60
	v_exp_f32_e32 v61, v61
	v_exp_f32_e32 v62, v62
	v_exp_f32_e32 v63, v63
	v_exp_f32_e32 v64, v64
	v_exp_f32_e32 v65, v65
	v_add_f32_e32 v104, v104, v58
	v_add_f32_e32 v106, v106, v59
	v_add_f32_e32 v104, v104, v60
	v_add_f32_e32 v106, v106, v61
	v_add_f32_e32 v104, v104, v62
	v_add_f32_e32 v106, v106, v63
	v_add_f32_e32 v104, v104, v64
	v_add_f32_e32 v106, v106, v65
	v_cvt_pk_bf16_f32 v172, v58, v59
	v_cvt_pk_bf16_f32 v173, v60, v61
	v_cvt_pk_bf16_f32 v174, v62, v63
	v_cvt_pk_bf16_f32 v175, v64, v65
	v_add_f32_e32 v104, v104, v106
	v_add_f32_e32 v114, v114, v104
	v_mfma_f32_32x32x16_bf16 v[18:33], v[210:213], v[172:175], v[18:33]
	v_mfma_f32_32x32x16_bf16 v[2:17], v[238:241], v[172:175], v[2:17]
	s_branch .Lfx_contB

.Lfx_contB:
	s_cmp_ge_i32 s13, s9
	s_cbranch_scc1 .LBB0_840
	ds_read_b128 v[116:119], v113 offset:18432
	ds_read_b128 v[120:123], v113 offset:18464
	ds_read_b128 v[124:127], v113 offset:18496
	ds_read_b128 v[182:185], v113 offset:18528
	ds_read_b128 v[186:189], v113 offset:23040
	ds_read_b128 v[190:193], v113 offset:23072
	ds_read_b128 v[242:245], v113 offset:23104
	ds_read_b128 v[246:249], v113 offset:23136
	v_sub_f32_e32 v1, v105, v112
	s_nop 0
	v_subrev_f32_dpp v34, v130, v1 row_newbcast:0 row_mask:0xf bank_mask:0xf
	v_subrev_f32_dpp v35, v130, v1 row_newbcast:1 row_mask:0xf bank_mask:0xf
	v_subrev_f32_dpp v36, v130, v1 row_newbcast:2 row_mask:0xf bank_mask:0xf
	v_subrev_f32_dpp v37, v130, v1 row_newbcast:3 row_mask:0xf bank_mask:0xf
	v_subrev_f32_dpp v38, v130, v1 row_newbcast:4 row_mask:0xf bank_mask:0xf
	v_subrev_f32_dpp v39, v130, v1 row_newbcast:5 row_mask:0xf bank_mask:0xf
	v_subrev_f32_dpp v40, v130, v1 row_newbcast:6 row_mask:0xf bank_mask:0xf
	v_subrev_f32_dpp v41, v130, v1 row_newbcast:7 row_mask:0xf bank_mask:0xf
	v_subrev_f32_dpp v42, v130, v1 row_newbcast:8 row_mask:0xf bank_mask:0xf
	v_subrev_f32_dpp v43, v130, v1 row_newbcast:9 row_mask:0xf bank_mask:0xf
	v_subrev_f32_dpp v44, v130, v1 row_newbcast:10 row_mask:0xf bank_mask:0xf
	v_subrev_f32_dpp v45, v130, v1 row_newbcast:11 row_mask:0xf bank_mask:0xf
	v_subrev_f32_dpp v46, v130, v1 row_newbcast:12 row_mask:0xf bank_mask:0xf
	v_subrev_f32_dpp v47, v130, v1 row_newbcast:13 row_mask:0xf bank_mask:0xf
	v_subrev_f32_dpp v48, v130, v1 row_newbcast:14 row_mask:0xf bank_mask:0xf
	v_subrev_f32_dpp v49, v130, v1 row_newbcast:15 row_mask:0xf bank_mask:0xf
	s_waitcnt lgkmcnt(4)
	s_nop 0
	v_mfma_f32_32x32x16_bf16 v[34:49], v[116:119], v[66:69], v[34:49]
	v_subrev_f32_dpp v50, v131, v1 row_newbcast:0 row_mask:0xf bank_mask:0xf
	v_subrev_f32_dpp v51, v131, v1 row_newbcast:1 row_mask:0xf bank_mask:0xf
	v_subrev_f32_dpp v52, v131, v1 row_newbcast:2 row_mask:0xf bank_mask:0xf
	v_subrev_f32_dpp v53, v131, v1 row_newbcast:3 row_mask:0xf bank_mask:0xf
	s_waitcnt lgkmcnt(4)
	v_mfma_f32_32x32x16_bf16 v[34:49], v[120:123], v[70:73], v[34:49]
	v_subrev_f32_dpp v54, v131, v1 row_newbcast:4 row_mask:0xf bank_mask:0xf
	v_subrev_f32_dpp v55, v131, v1 row_newbcast:5 row_mask:0xf bank_mask:0xf
	v_subrev_f32_dpp v56, v131, v1 row_newbcast:6 row_mask:0xf bank_mask:0xf
	v_subrev_f32_dpp v57, v131, v1 row_newbcast:7 row_mask:0xf bank_mask:0xf
	s_waitcnt lgkmcnt(4)
	v_mfma_f32_32x32x16_bf16 v[34:49], v[124:127], v[74:77], v[34:49]
	v_subrev_f32_dpp v58, v131, v1 row_newbcast:8 row_mask:0xf bank_mask:0xf
	v_subrev_f32_dpp v59, v131, v1 row_newbcast:9 row_mask:0xf bank_mask:0xf
	v_subrev_f32_dpp v60, v131, v1 row_newbcast:10 row_mask:0xf bank_mask:0xf
	v_subrev_f32_dpp v61, v131, v1 row_newbcast:11 row_mask:0xf bank_mask:0xf
	s_waitcnt lgkmcnt(0)
	v_mfma_f32_32x32x16_bf16 v[34:49], v[182:185], v[78:81], v[34:49]
	v_subrev_f32_dpp v62, v131, v1 row_newbcast:12 row_mask:0xf bank_mask:0xf
	v_subrev_f32_dpp v63, v131, v1 row_newbcast:13 row_mask:0xf bank_mask:0xf
	v_subrev_f32_dpp v64, v131, v1 row_newbcast:14 row_mask:0xf bank_mask:0xf
	v_subrev_f32_dpp v65, v131, v1 row_newbcast:15 row_mask:0xf bank_mask:0xf
	s_nop 1
	v_mfma_f32_32x32x16_bf16 v[50:65], v[186:189], v[66:69], v[50:65]
	ds_read_b64_tr_b16 v[198:199], v108 offset:27648
	ds_read_b64_tr_b16 v[200:201], v108 offset:28800
	ds_read_b64_tr_b16 v[202:203], v108 offset:29952
	ds_read_b64_tr_b16 v[204:205], v108 offset:31104
	v_mfma_f32_32x32x16_bf16 v[50:65], v[190:193], v[70:73], v[50:65]
	ds_read_b64_tr_b16 v[206:207], v108 offset:32256
	ds_read_b64_tr_b16 v[208:209], v108 offset:33408
	ds_read_b64_tr_b16 v[210:211], v108 offset:34560
	ds_read_b64_tr_b16 v[212:213], v108 offset:35712
	v_mfma_f32_32x32x16_bf16 v[50:65], v[242:245], v[74:77], v[50:65]
	ds_read_b64_tr_b16 v[214:215], v108 offset:27712
	ds_read_b64_tr_b16 v[216:217], v108 offset:28864
	ds_read_b64_tr_b16 v[218:219], v108 offset:30016
	ds_read_b64_tr_b16 v[220:221], v108 offset:31168
	v_mfma_f32_32x32x16_bf16 v[50:65], v[246:249], v[78:81], v[50:65]
	ds_read_b64_tr_b16 v[234:235], v108 offset:32320
	ds_read_b64_tr_b16 v[236:237], v108 offset:33472
	ds_read_b64_tr_b16 v[238:239], v108 offset:34624
	ds_read_b64_tr_b16 v[240:241], v108 offset:35776
	s_nop 1
	ds_read_b32 v128, v110 offset:512
	ds_read_b32 v129, v110 offset:640
	s_cmp_lg_u32 s11, s13
	s_cbranch_scc1 .LBB0_835
	v_subrev_u32_e32 v104, 27, v111
	v_subrev_u32_e32 v1, 59, v111
	v_cmp_le_i32_e32 vcc, v104, v102
	s_nop 7
	v_cndmask_b32_e32 v50, v232, v50, vcc
	v_cmp_lt_i32_e32 vcc, v1, v102
	s_nop 1
	v_cndmask_b32_e32 v35, v232, v35, vcc
	v_cmp_le_i32_e32 vcc, v1, v102
	v_subrev_u32_e32 v1, 26, v111
	s_nop 0
	v_cndmask_b32_e32 v34, v232, v34, vcc
	v_cmp_le_i32_e32 vcc, v1, v102
	v_subrev_u32_e32 v1, 57, v111
	s_nop 0
	v_cndmask_b32_e32 v51, v232, v51, vcc
	v_cmp_le_i32_e32 vcc, v1, v102
	v_subrev_u32_e32 v1, 25, v111
	s_nop 0
	v_cndmask_b32_e32 v36, v232, v36, vcc
	v_cmp_le_i32_e32 vcc, v1, v102
	v_subrev_u32_e32 v1, 56, v111
	s_nop 0
	v_cndmask_b32_e32 v52, v232, v52, vcc
	v_cmp_le_i32_e32 vcc, v1, v102
	v_subrev_u32_e32 v1, 24, v111
	s_nop 0
	v_cndmask_b32_e32 v37, v232, v37, vcc
	v_cmp_le_i32_e32 vcc, v1, v102
	v_subrev_u32_e32 v1, 51, v111
	s_nop 0
	v_cndmask_b32_e32 v53, v232, v53, vcc
	v_cmp_le_i32_e32 vcc, v1, v102
	v_subrev_u32_e32 v1, 19, v111
	s_nop 0
	v_cndmask_b32_e32 v38, v232, v38, vcc
	v_cmp_le_i32_e32 vcc, v1, v102
	v_subrev_u32_e32 v1, 50, v111
	s_nop 0
	v_cndmask_b32_e32 v54, v232, v54, vcc
	v_cmp_le_i32_e32 vcc, v1, v102
	v_subrev_u32_e32 v1, 18, v111
	s_nop 0
	v_cndmask_b32_e32 v39, v232, v39, vcc
	v_cmp_le_i32_e32 vcc, v1, v102
	v_subrev_u32_e32 v1, 49, v111
	s_nop 0
	v_cndmask_b32_e32 v55, v232, v55, vcc
	v_cmp_le_i32_e32 vcc, v1, v102
	v_subrev_u32_e32 v1, 17, v111
	s_nop 0
	v_cndmask_b32_e32 v40, v232, v40, vcc
	v_cmp_le_i32_e32 vcc, v1, v102
	v_subrev_u32_e32 v1, 48, v111
	s_nop 0
	v_cndmask_b32_e32 v56, v232, v56, vcc
	v_cmp_le_i32_e32 vcc, v1, v102
	v_add_u32_e32 v1, -16, v111
	s_nop 0
	v_cndmask_b32_e32 v41, v232, v41, vcc
	v_cmp_le_i32_e32 vcc, v1, v102
	v_subrev_u32_e32 v1, 43, v111
	s_nop 0
	v_cndmask_b32_e32 v57, v232, v57, vcc
	v_cmp_le_i32_e32 vcc, v1, v102
	v_add_u32_e32 v1, -11, v111
	s_nop 0
	v_cndmask_b32_e32 v42, v232, v42, vcc
	v_cmp_le_i32_e32 vcc, v1, v102
	v_subrev_u32_e32 v1, 42, v111
	s_nop 0
	v_cndmask_b32_e32 v58, v232, v58, vcc
	v_cmp_le_i32_e32 vcc, v1, v102
	v_add_u32_e32 v1, -10, v111
	s_nop 0
	v_cndmask_b32_e32 v43, v232, v43, vcc
	v_cmp_le_i32_e32 vcc, v1, v102
	v_subrev_u32_e32 v1, 41, v111
	s_nop 0
	v_cndmask_b32_e32 v59, v232, v59, vcc
	v_cmp_le_i32_e32 vcc, v1, v102
	v_add_u32_e32 v1, -9, v111
	s_nop 0
	v_cndmask_b32_e32 v44, v232, v44, vcc
	v_cmp_le_i32_e32 vcc, v1, v102
	v_subrev_u32_e32 v1, 40, v111
	s_nop 0
	v_cndmask_b32_e32 v60, v232, v60, vcc
	v_cmp_le_i32_e32 vcc, v1, v102
	v_add_u32_e32 v1, -8, v111
	s_nop 0
	v_cndmask_b32_e32 v45, v232, v45, vcc
	v_cmp_le_i32_e32 vcc, v1, v102
	v_subrev_u32_e32 v1, 35, v111
	s_nop 0
	v_cndmask_b32_e32 v61, v232, v61, vcc
	v_cmp_le_i32_e32 vcc, v1, v102
	v_add_u32_e32 v1, -3, v111
	s_nop 0
	v_cndmask_b32_e32 v46, v232, v46, vcc
	v_cmp_le_i32_e32 vcc, v1, v102
	v_subrev_u32_e32 v1, 34, v111
	s_nop 0
	v_cndmask_b32_e32 v62, v232, v62, vcc
	v_cmp_le_i32_e32 vcc, v1, v102
	v_add_u32_e32 v1, -2, v111
	s_nop 0
	v_cndmask_b32_e32 v47, v232, v47, vcc
	v_cmp_le_i32_e32 vcc, v1, v102
	v_subrev_u32_e32 v1, 33, v111
	s_nop 0
	v_cndmask_b32_e32 v63, v232, v63, vcc
	v_cmp_le_i32_e32 vcc, v1, v102
	v_add_u32_e32 v1, -1, v111
	s_nop 0
	v_cndmask_b32_e32 v48, v232, v48, vcc
	v_cmp_le_i32_e32 vcc, v1, v102
	v_subrev_u32_e32 v1, 32, v111
	s_nop 0
	v_cndmask_b32_e32 v64, v232, v64, vcc
	v_cmp_le_i32_e32 vcc, v1, v102
	s_nop 1
	v_cndmask_b32_e32 v49, v232, v49, vcc
	v_cmp_le_i32_e32 vcc, v111, v102
	s_nop 1
	v_cndmask_b32_e32 v65, v232, v65, vcc

; #define LAS __attribute__((address_space(3)))
; #define STAGE_TILE(bufi, KR, VR) do { LAS bf16_t* Ks_ = (LAS bf16_t*)(lds + (bufi) * 18432); LAS bf16_t* Vs_ = (LAS bf16_t*)(lds + (bufi) * 18432 + 9216); \
;         *(LAS u32x4*)(Ks_ + skr * 72 + sch * 8) = KR; *(LAS u32x4*)(Vs_ + skr * 72 + sch * 8) = VR; } while (0)
; template <int MODE> ...
;     ...
;         COMPUTE_TILE(TILE_OF(it + 1), 1);
;         STAGE_TILE(0, kreg, vreg);
;         __syncthreads();
;         if (MODE == 1) { const u32x4 fa = *(const LAS u32x4*)flags, fb = *(const LAS u32x4*)(flags + 4); if ((fa.x & fa.y & fa.z & fa.w & fb.x & fb.y & fb.z & fb.w) != 0u) stop = true; }
;     }
.LBB0_839:
	s_waitcnt vmcnt(3)
	ds_write_b128 v107, v[90:93]
	s_waitcnt vmcnt(2)
	ds_write_b128 v107, v[94:97] offset:9216
	s_waitcnt lgkmcnt(0)
	s_barrier
	v_exp_f32_e32 v34, v34
	v_exp_f32_e32 v35, v35
	v_exp_f32_e32 v36, v36
	v_exp_f32_e32 v37, v37
	v_exp_f32_e32 v38, v38
	v_exp_f32_e32 v39, v39
	v_exp_f32_e32 v40, v40
	v_exp_f32_e32 v41, v41
	v_add_f32_e32 v104, v34, v35
	v_add_f32_e32 v106, v36, v37
	v_add_f32_e32 v104, v104, v38
	v_add_f32_e32 v106, v106, v39
	v_add_f32_e32 v104, v104, v40
	v_add_f32_e32 v106, v106, v41
	v_cvt_pk_bf16_f32 v132, v34, v35
	v_cvt_pk_bf16_f32 v133, v36, v37
	v_cvt_pk_bf16_f32 v134, v38, v39
	v_cvt_pk_bf16_f32 v135, v40, v41
	v_exp_f32_e32 v42, v42
	v_exp_f32_e32 v43, v43
	s_waitcnt lgkmcnt(0)
	v_mfma_f32_32x32x16_bf16 v[18:33], v[198:201], v[132:135], v[18:33]
	v_mfma_f32_32x32x16_bf16 v[2:17], v[214:217], v[132:135], v[2:17]
	v_exp_f32_e32 v44, v44
	v_exp_f32_e32 v45, v45
	v_exp_f32_e32 v46, v46
	v_exp_f32_e32 v47, v47
	v_exp_f32_e32 v48, v48
	v_exp_f32_e32 v49, v49
	v_add_f32_e32 v104, v104, v42
	v_add_f32_e32 v106, v106, v43
	v_add_f32_e32 v104, v104, v44
	v_add_f32_e32 v106, v106, v45
	v_add_f32_e32 v104, v104, v46
	v_add_f32_e32 v106, v106, v47
	v_add_f32_e32 v104, v104, v48
	v_add_f32_e32 v106, v106, v49
	v_cvt_pk_bf16_f32 v148, v42, v43
	v_cvt_pk_bf16_f32 v149, v44, v45
	v_cvt_pk_bf16_f32 v150, v46, v47
	v_cvt_pk_bf16_f32 v151, v48, v49
	v_exp_f32_e32 v50, v50
	v_exp_f32_e32 v51, v51
	v_mfma_f32_32x32x16_bf16 v[18:33], v[202:205], v[148:151], v[18:33]
	v_mfma_f32_32x32x16_bf16 v[2:17], v[218:221], v[148:151], v[2:17]
	v_exp_f32_e32 v52, v52
	v_exp_f32_e32 v53, v53
	v_exp_f32_e32 v54, v54
	v_exp_f32_e32 v55, v55
	v_exp_f32_e32 v56, v56
	v_exp_f32_e32 v57, v57
	v_add_f32_e32 v104, v104, v50
	v_add_f32_e32 v106, v106, v51
	v_add_f32_e32 v104, v104, v52
	v_add_f32_e32 v106, v106, v53
	v_add_f32_e32 v104, v104, v54
	v_add_f32_e32 v106, v106, v55
	v_add_f32_e32 v104, v104, v56
	v_add_f32_e32 v106, v106, v57
	v_cvt_pk_bf16_f32 v156, v50, v51
	v_cvt_pk_bf16_f32 v157, v52, v53
	v_cvt_pk_bf16_f32 v158, v54, v55
	v_cvt_pk_bf16_f32 v159, v56, v57
	v_exp_f32_e32 v58, v58
	v_exp_f32_e32 v59, v59
	v_mfma_f32_32x32x16_bf16 v[18:33], v[206:209], v[156:159], v[18:33]
	v_mfma_f32_32x32x16_bf16 v[2:17], v[234:237], v[156:159], v[2:17]
	v_exp_f32_e32 v60, v60
	v_exp_f32_e32 v61, v61
	v_exp_f32_e32 v62, v62
	v_exp_f32_e32 v63, v63
	v_exp_f32_e32 v64, v64
	v_exp_f32_e32 v65, v65
	v_add_f32_e32 v104, v104, v58
	v_add_f32_e32 v106, v106, v59
	v_add_f32_e32 v104, v104, v60
	v_add_f32_e32 v106, v106, v61
	v_add_f32_e32 v104, v104, v62
	v_add_f32_e32 v106, v106, v63
	v_add_f32_e32 v104, v104, v64
	v_add_f32_e32 v106, v106, v65
	v_cvt_pk_bf16_f32 v172, v58, v59
	v_cvt_pk_bf16_f32 v173, v60, v61
	v_cvt_pk_bf16_f32 v174, v62, v63
	v_cvt_pk_bf16_f32 v175, v64, v65
	v_add_f32_e32 v104, v104, v106
	v_add_f32_e32 v114, v114, v104
	v_mfma_f32_32x32x16_bf16 v[18:33], v[210:213], v[172:175], v[18:33]
	v_mfma_f32_32x32x16_bf16 v[2:17], v[238:241], v[172:175], v[2:17]
	s_branch .Lfx_contL
.LBB0_840:
	s_waitcnt vmcnt(3)
	ds_write_b128 v107, v[90:93]
	s_waitcnt vmcnt(2)
	ds_write_b128 v107, v[94:97] offset:9216
	s_waitcnt lgkmcnt(0)
	s_barrier
.Lfx_contL:
	v_add_u32_e32 v110, 0x200, v110
	s_cmp_lt_u32 s12, s8
	v_add_u32_e32 v111, 0x80, v111
	s_cbranch_scc0 .LBB0_339
	s_mov_b32 s13, s12
	s_branch .LBB0_824
